# v25: v24 + P0: 9-row waves hand their second transpose item to 8-row waves
# speedup vs baseline: 1.0023x; 1.0017x over previous
; __global__ void __launch_bounds__(512, 2) mega_fwd(Args args) {
;     ...
;         for (int it = gw; it < NIT; it += NGW) {
;             int r = it;
;             if (r < I_IN) { transpose_mat(w_in, D, INW, WT_IN, 0, 0, nullptr, nullptr, r, scr, lane); continue; } r -= I_IN;
;             if (r < I_OUT) { transpose_mat(w_out, D, D, WT_OUT, 0, 0, nullptr, nullptr, r, scr, lane); continue; } r -= I_OUT;
;             if (r < I_MQ) { transpose_mat(w_mem_q, D, MEMW, WT_MQ, 0, 0, nullptr, norm_mem, r, scr, lane); continue; } r -= I_MQ;
;             if (r < I_MQ) { transpose_mat(w_mem_k, D, MEMW, WT_MKV, 0, 0, nullptr, nullptr, r, scr, lane); continue; } r -= I_MQ;
;             if (r < I_MQ) { transpose_mat(w_mem_v, D, MEMW, WT_MKV, 0, 512, nullptr, nullptr, r, scr, lane); continue; } r -= I_MQ;
;             if (r < I_MO) { transpose_mat(w_mem_o, MEMW, D, WT_MO, 0, 0, nullptr, nullptr, r, scr, lane); continue; } r -= I_MO;
;             { const int g = r / I_PL; transpose_mat(w_pool + (size_t)g * 65536, 256, 256, WT_POOL, 0, g * 256, pool_scale, nullptr, r % I_PL, scr, lane); }
;         }
.LBB0_8:
	s_add_i32 s79, s79, s14
	s_cmpk_lt_i32 s79, 0x1000
	s_cbranch_scc0 .Lp0_third
	s_cmpk_lt_i32 s79, 0x980
	s_cbranch_scc1 .LBB0_65
	s_branch .Lp0_norm
.Lp0_third:
	s_cmpk_lt_i32 s79, 0x1640
	s_cbranch_scc1 .LBB0_65
	s_cmpk_lt_i32 s79, 0x17c0
	s_cbranch_scc0 .Lp0_pool
	s_sub_i32 s79, s79, 0xe40
	s_branch .Lp0_norm
.Lp0_pool:
	s_sub_i32 s79, 0x27ff, s79
	s_cmpk_lt_i32 s79, 0x1000
	s_cbranch_scc1 .LBB0_65
